# v30 + down/out-projection epilogues: the 48 cross-row ds_bpermute steps of the sum-of-squares reductions replaced by v_permlane16/32_swap of a copy (no LDS round trip, same bits)
# speedup vs baseline: 1.0038x; 1.0038x over previous
.LBB0_346:
	s_nop 0
	v_and_b32_e32 v147, 0xffff0000, v154
	v_lshlrev_b32_e32 v146, 16, v154
	v_and_b32_e32 v149, 0xffff0000, v155
	v_mul_f32_e32 v147, v147, v147
	v_lshlrev_b32_e32 v148, 16, v155
	v_fmac_f32_e32 v147, v146, v146
	v_mul_f32_e32 v146, v149, v149
	v_lshlrev_b32_e32 v154, 16, v156
	v_and_b32_e32 v155, 0xffff0000, v156
	v_lshlrev_b32_e32 v156, 16, v157
	v_and_b32_e32 v157, 0xffff0000, v157
	v_fmac_f32_e32 v146, v148, v148
	v_add_f32_e32 v146, v147, v146
	v_mul_f32_e32 v147, v155, v155
	v_mul_f32_e32 v148, v157, v157
	v_fmac_f32_e32 v147, v154, v154
	v_fmac_f32_e32 v148, v156, v156
	v_add_f32_e32 v147, v147, v148
	v_add_f32_e32 v146, v146, v147
	v_lshlrev_b32_e32 v147, 16, v138
	v_and_b32_e32 v138, 0xffff0000, v138
	v_lshlrev_b32_e32 v148, 16, v139
	v_and_b32_e32 v139, 0xffff0000, v139
	v_mul_f32_e32 v138, v138, v138
	v_mul_f32_e32 v139, v139, v139
	v_lshlrev_b32_e32 v149, 16, v140
	v_and_b32_e32 v140, 0xffff0000, v140
	v_lshlrev_b32_e32 v154, 16, v141
	v_and_b32_e32 v141, 0xffff0000, v141
	v_fmac_f32_e32 v138, v147, v147
	v_fmac_f32_e32 v139, v148, v148
	v_add_f32_e32 v138, v138, v139
	v_mul_f32_e32 v139, v140, v140
	v_mul_f32_e32 v140, v141, v141
	v_fmac_f32_e32 v139, v149, v149
	v_fmac_f32_e32 v140, v154, v154
	v_add_f32_e32 v139, v139, v140
	v_add_f32_e32 v138, v138, v139
	v_mov_b32_e32 v139, v248
	v_add_f32_e32 v138, v146, v138
	v_mov_b32_e32 v139, v138
	s_nop 1
	v_permlane16_swap_b32_e32 v139, v138
	s_lshl_b32 s26, s51, 2
	s_ashr_i32 s27, s26, 31
	s_waitcnt lgkmcnt(0)
	v_add_f32_e32 v138, v138, v139
	v_mov_b32_e32 v139, v248
	s_nop 0
	v_mov_b32_e32 v139, v138
	s_nop 1
	v_permlane32_swap_b32_e32 v139, v138
	s_and_saveexec_b64 s[28:29], s[2:3]
	s_cbranch_execz .LBB0_348
	v_lshlrev_b64 v[140:141], 6, v[242:243]
	v_lshl_add_u64 v[140:141], s[10:11], 0, v[140:141]
	v_lshl_add_u64 v[140:141], s[26:27], 2, v[140:141]
	s_lshl_b32 s60, s44, 2
	v_lshl_add_u64 v[140:141], v[140:141], 0, s[60:61]
	s_waitcnt lgkmcnt(0)
	v_add_f32_e32 v138, v138, v139
	global_store_dword v[140:141], v138, off

.LBB0_352:
	s_nop 0
	v_and_b32_e32 v119, 0xffff0000, v130
	v_lshlrev_b32_e32 v118, 16, v130
	v_and_b32_e32 v121, 0xffff0000, v131
	v_mul_f32_e32 v119, v119, v119
	v_lshlrev_b32_e32 v120, 16, v131
	v_fmac_f32_e32 v119, v118, v118
	v_mul_f32_e32 v118, v121, v121
	v_lshlrev_b32_e32 v130, 16, v132
	v_and_b32_e32 v131, 0xffff0000, v132
	v_lshlrev_b32_e32 v132, 16, v133
	v_and_b32_e32 v133, 0xffff0000, v133
	v_fmac_f32_e32 v118, v120, v120
	v_add_f32_e32 v118, v119, v118
	v_mul_f32_e32 v119, v131, v131
	v_mul_f32_e32 v120, v133, v133
	v_fmac_f32_e32 v119, v130, v130
	v_fmac_f32_e32 v120, v132, v132
	v_add_f32_e32 v119, v119, v120
	v_add_f32_e32 v118, v118, v119
	v_lshlrev_b32_e32 v119, 16, v114
	v_and_b32_e32 v114, 0xffff0000, v114
	v_lshlrev_b32_e32 v120, 16, v115
	v_and_b32_e32 v115, 0xffff0000, v115
	v_mul_f32_e32 v114, v114, v114
	v_mul_f32_e32 v115, v115, v115
	v_lshlrev_b32_e32 v121, 16, v116
	v_and_b32_e32 v116, 0xffff0000, v116
	v_lshlrev_b32_e32 v130, 16, v117
	v_and_b32_e32 v117, 0xffff0000, v117
	v_fmac_f32_e32 v114, v119, v119
	v_fmac_f32_e32 v115, v120, v120
	v_add_f32_e32 v114, v114, v115
	v_mul_f32_e32 v115, v116, v116
	v_mul_f32_e32 v116, v117, v117
	v_fmac_f32_e32 v115, v121, v121
	v_fmac_f32_e32 v116, v130, v130
	v_add_f32_e32 v115, v115, v116
	v_add_f32_e32 v114, v114, v115
	v_mov_b32_e32 v115, v248
	v_add_f32_e32 v114, v118, v114
	v_mov_b32_e32 v115, v114
	s_nop 1
	v_permlane16_swap_b32_e32 v115, v114
	s_waitcnt lgkmcnt(0)
	v_add_f32_e32 v114, v114, v115
	v_mov_b32_e32 v115, v248
	s_nop 0
	v_mov_b32_e32 v115, v114
	s_nop 1
	v_permlane32_swap_b32_e32 v115, v114
	s_and_saveexec_b64 s[28:29], s[2:3]
	s_cbranch_execz .LBB0_354
	v_lshlrev_b64 v[116:117], 6, v[238:239]
	v_lshl_add_u64 v[116:117], s[10:11], 0, v[116:117]
	v_lshl_add_u64 v[116:117], s[26:27], 2, v[116:117]
	s_lshl_b32 s60, s44, 2
	v_lshl_add_u64 v[116:117], v[116:117], 0, s[60:61]
	s_waitcnt lgkmcnt(0)
	v_add_f32_e32 v114, v114, v115
	global_store_dword v[116:117], v114, off

.LBB0_358:
	s_nop 0
	v_and_b32_e32 v93, 0xffff0000, v102
	v_lshlrev_b32_e32 v92, 16, v102
	v_and_b32_e32 v95, 0xffff0000, v103
	v_mul_f32_e32 v93, v93, v93
	v_lshlrev_b32_e32 v94, 16, v103
	v_fmac_f32_e32 v93, v92, v92
	v_mul_f32_e32 v92, v95, v95
	v_lshlrev_b32_e32 v102, 16, v104
	v_and_b32_e32 v103, 0xffff0000, v104
	v_lshlrev_b32_e32 v104, 16, v105
	v_and_b32_e32 v105, 0xffff0000, v105
	v_fmac_f32_e32 v92, v94, v94
	v_add_f32_e32 v92, v93, v92
	v_mul_f32_e32 v93, v103, v103
	v_mul_f32_e32 v94, v105, v105
	v_fmac_f32_e32 v93, v102, v102
	v_fmac_f32_e32 v94, v104, v104
	v_add_f32_e32 v93, v93, v94
	v_add_f32_e32 v92, v92, v93
	v_lshlrev_b32_e32 v93, 16, v88
	v_and_b32_e32 v88, 0xffff0000, v88
	v_lshlrev_b32_e32 v94, 16, v89
	v_and_b32_e32 v89, 0xffff0000, v89
	v_mul_f32_e32 v88, v88, v88
	v_mul_f32_e32 v89, v89, v89
	v_lshlrev_b32_e32 v95, 16, v90
	v_and_b32_e32 v90, 0xffff0000, v90
	v_lshlrev_b32_e32 v102, 16, v91
	v_and_b32_e32 v91, 0xffff0000, v91
	v_fmac_f32_e32 v88, v93, v93
	v_fmac_f32_e32 v89, v94, v94
	v_add_f32_e32 v88, v88, v89
	v_mul_f32_e32 v89, v90, v90
	v_mul_f32_e32 v90, v91, v91
	v_fmac_f32_e32 v89, v95, v95
	v_fmac_f32_e32 v90, v102, v102
	v_add_f32_e32 v89, v89, v90
	v_add_f32_e32 v88, v88, v89
	v_mov_b32_e32 v89, v248
	v_add_f32_e32 v88, v92, v88
	v_mov_b32_e32 v89, v88
	s_nop 1
	v_permlane16_swap_b32_e32 v89, v88
	s_waitcnt lgkmcnt(0)
	v_add_f32_e32 v88, v88, v89
	v_mov_b32_e32 v89, v248
	s_nop 0
	v_mov_b32_e32 v89, v88
	s_nop 1
	v_permlane32_swap_b32_e32 v89, v88
	s_and_saveexec_b64 s[28:29], s[2:3]
	s_cbranch_execz .LBB0_360
	v_lshlrev_b64 v[90:91], 6, v[234:235]
	v_lshl_add_u64 v[90:91], s[10:11], 0, v[90:91]
	v_lshl_add_u64 v[90:91], s[26:27], 2, v[90:91]
	s_lshl_b32 s60, s44, 2
	v_lshl_add_u64 v[90:91], v[90:91], 0, s[60:61]
	s_waitcnt lgkmcnt(0)
	v_add_f32_e32 v88, v88, v89
	global_store_dword v[90:91], v88, off

.LBB0_364:
	s_nop 0
	v_and_b32_e32 v69, 0xffff0000, v76
	v_lshlrev_b32_e32 v68, 16, v76
	v_and_b32_e32 v71, 0xffff0000, v77
	v_mul_f32_e32 v69, v69, v69
	v_lshlrev_b32_e32 v70, 16, v77
	v_fmac_f32_e32 v69, v68, v68
	v_mul_f32_e32 v68, v71, v71
	v_lshlrev_b32_e32 v76, 16, v78
	v_and_b32_e32 v77, 0xffff0000, v78
	v_lshlrev_b32_e32 v78, 16, v79
	v_and_b32_e32 v79, 0xffff0000, v79
	v_fmac_f32_e32 v68, v70, v70
	v_add_f32_e32 v68, v69, v68
	v_mul_f32_e32 v69, v77, v77
	v_mul_f32_e32 v70, v79, v79
	v_fmac_f32_e32 v69, v76, v76
	v_fmac_f32_e32 v70, v78, v78
	v_add_f32_e32 v69, v69, v70
	v_add_f32_e32 v68, v68, v69
	v_lshlrev_b32_e32 v69, 16, v64
	v_and_b32_e32 v64, 0xffff0000, v64
	v_lshlrev_b32_e32 v70, 16, v65
	v_and_b32_e32 v65, 0xffff0000, v65
	v_mul_f32_e32 v64, v64, v64
	v_mul_f32_e32 v65, v65, v65
	v_lshlrev_b32_e32 v71, 16, v66
	v_and_b32_e32 v66, 0xffff0000, v66
	v_lshlrev_b32_e32 v76, 16, v67
	v_and_b32_e32 v67, 0xffff0000, v67
	v_fmac_f32_e32 v64, v69, v69
	v_fmac_f32_e32 v65, v70, v70
	v_add_f32_e32 v64, v64, v65
	v_mul_f32_e32 v65, v66, v66
	v_mul_f32_e32 v66, v67, v67
	v_fmac_f32_e32 v65, v71, v71
	v_fmac_f32_e32 v66, v76, v76
	v_add_f32_e32 v65, v65, v66
	v_add_f32_e32 v64, v64, v65
	v_mov_b32_e32 v65, v248
	v_add_f32_e32 v64, v68, v64
	v_mov_b32_e32 v65, v64
	s_nop 1
	v_permlane16_swap_b32_e32 v65, v64
	s_waitcnt lgkmcnt(0)
	v_add_f32_e32 v64, v64, v65
	v_mov_b32_e32 v65, v248
	s_nop 0
	v_mov_b32_e32 v65, v64
	s_nop 1
	v_permlane32_swap_b32_e32 v65, v64
	s_and_saveexec_b64 s[28:29], s[2:3]
	s_cbranch_execz .LBB0_366
	v_lshlrev_b64 v[66:67], 6, v[230:231]
	v_lshl_add_u64 v[66:67], s[10:11], 0, v[66:67]
	v_lshl_add_u64 v[66:67], s[26:27], 2, v[66:67]
	s_lshl_b32 s60, s44, 2
	v_lshl_add_u64 v[66:67], v[66:67], 0, s[60:61]
	s_waitcnt lgkmcnt(0)
	v_add_f32_e32 v64, v64, v65
	global_store_dword v[66:67], v64, off

.LBB0_370:
	s_nop 0
	v_and_b32_e32 v53, 0xffff0000, v56
	v_lshlrev_b32_e32 v52, 16, v56
	v_and_b32_e32 v55, 0xffff0000, v57
	v_mul_f32_e32 v53, v53, v53
	v_lshlrev_b32_e32 v54, 16, v57
	v_fmac_f32_e32 v53, v52, v52
	v_mul_f32_e32 v52, v55, v55
	v_lshlrev_b32_e32 v56, 16, v58
	v_and_b32_e32 v57, 0xffff0000, v58
	v_lshlrev_b32_e32 v58, 16, v59
	v_and_b32_e32 v59, 0xffff0000, v59
	v_fmac_f32_e32 v52, v54, v54
	v_add_f32_e32 v52, v53, v52
	v_mul_f32_e32 v53, v57, v57
	v_mul_f32_e32 v54, v59, v59
	v_fmac_f32_e32 v53, v56, v56
	v_fmac_f32_e32 v54, v58, v58
	v_add_f32_e32 v53, v53, v54
	v_add_f32_e32 v52, v52, v53
	v_lshlrev_b32_e32 v53, 16, v48
	v_and_b32_e32 v48, 0xffff0000, v48
	v_lshlrev_b32_e32 v54, 16, v49
	v_and_b32_e32 v49, 0xffff0000, v49
	v_mul_f32_e32 v48, v48, v48
	v_mul_f32_e32 v49, v49, v49
	v_lshlrev_b32_e32 v55, 16, v50
	v_and_b32_e32 v50, 0xffff0000, v50
	v_lshlrev_b32_e32 v56, 16, v51
	v_and_b32_e32 v51, 0xffff0000, v51
	v_fmac_f32_e32 v48, v53, v53
	v_fmac_f32_e32 v49, v54, v54
	v_add_f32_e32 v48, v48, v49
	v_mul_f32_e32 v49, v50, v50
	v_mul_f32_e32 v50, v51, v51
	v_fmac_f32_e32 v49, v55, v55
	v_fmac_f32_e32 v50, v56, v56
	v_add_f32_e32 v49, v49, v50
	v_add_f32_e32 v48, v48, v49
	v_mov_b32_e32 v49, v248
	v_add_f32_e32 v48, v52, v48
	v_mov_b32_e32 v49, v48
	s_nop 1
	v_permlane16_swap_b32_e32 v49, v48
	s_waitcnt lgkmcnt(0)
	v_add_f32_e32 v48, v48, v49
	v_mov_b32_e32 v49, v248
	s_nop 0
	v_mov_b32_e32 v49, v48
	s_nop 1
	v_permlane32_swap_b32_e32 v49, v48
	s_and_saveexec_b64 s[28:29], s[2:3]
	s_cbranch_execz .LBB0_372
	v_lshlrev_b64 v[50:51], 6, v[226:227]
	v_lshl_add_u64 v[50:51], s[10:11], 0, v[50:51]
	v_lshl_add_u64 v[50:51], s[26:27], 2, v[50:51]
	s_lshl_b32 s60, s44, 2
	v_lshl_add_u64 v[50:51], v[50:51], 0, s[60:61]
	s_waitcnt lgkmcnt(0)
	v_add_f32_e32 v48, v48, v49
	global_store_dword v[50:51], v48, off

.LBB0_376:
	s_nop 0
	v_and_b32_e32 v37, 0xffff0000, v40
	v_lshlrev_b32_e32 v36, 16, v40
	v_and_b32_e32 v39, 0xffff0000, v41
	v_mul_f32_e32 v37, v37, v37
	v_lshlrev_b32_e32 v38, 16, v41
	v_fmac_f32_e32 v37, v36, v36
	v_mul_f32_e32 v36, v39, v39
	v_lshlrev_b32_e32 v40, 16, v42
	v_and_b32_e32 v41, 0xffff0000, v42
	v_lshlrev_b32_e32 v42, 16, v43
	v_and_b32_e32 v43, 0xffff0000, v43
	v_fmac_f32_e32 v36, v38, v38
	v_add_f32_e32 v36, v37, v36
	v_mul_f32_e32 v37, v41, v41
	v_mul_f32_e32 v38, v43, v43
	v_fmac_f32_e32 v37, v40, v40
	v_fmac_f32_e32 v38, v42, v42
	v_add_f32_e32 v37, v37, v38
	v_add_f32_e32 v36, v36, v37
	v_lshlrev_b32_e32 v37, 16, v32
	v_and_b32_e32 v32, 0xffff0000, v32
	v_lshlrev_b32_e32 v38, 16, v33
	v_and_b32_e32 v33, 0xffff0000, v33
	v_mul_f32_e32 v32, v32, v32
	v_mul_f32_e32 v33, v33, v33
	v_lshlrev_b32_e32 v39, 16, v34
	v_and_b32_e32 v34, 0xffff0000, v34
	v_lshlrev_b32_e32 v40, 16, v35
	v_and_b32_e32 v35, 0xffff0000, v35
	v_fmac_f32_e32 v32, v37, v37
	v_fmac_f32_e32 v33, v38, v38
	v_add_f32_e32 v32, v32, v33
	v_mul_f32_e32 v33, v34, v34
	v_mul_f32_e32 v34, v35, v35
	v_fmac_f32_e32 v33, v39, v39
	v_fmac_f32_e32 v34, v40, v40
	v_add_f32_e32 v33, v33, v34
	v_add_f32_e32 v32, v32, v33
	v_mov_b32_e32 v33, v248
	v_add_f32_e32 v32, v36, v32
	v_mov_b32_e32 v33, v32
	s_nop 1
	v_permlane16_swap_b32_e32 v33, v32
	s_waitcnt lgkmcnt(0)
	v_add_f32_e32 v32, v32, v33
	v_mov_b32_e32 v33, v248
	s_nop 0
	v_mov_b32_e32 v33, v32
	s_nop 1
	v_permlane32_swap_b32_e32 v33, v32
	s_and_saveexec_b64 s[28:29], s[2:3]
	s_cbranch_execz .LBB0_378
	v_lshlrev_b64 v[34:35], 6, v[222:223]
	v_lshl_add_u64 v[34:35], s[10:11], 0, v[34:35]
	v_lshl_add_u64 v[34:35], s[26:27], 2, v[34:35]
	s_lshl_b32 s60, s44, 2
	v_lshl_add_u64 v[34:35], v[34:35], 0, s[60:61]
	s_waitcnt lgkmcnt(0)
	v_add_f32_e32 v32, v32, v33
	global_store_dword v[34:35], v32, off

.LBB0_382:
	s_nop 0
	v_and_b32_e32 v21, 0xffff0000, v24
	v_lshlrev_b32_e32 v20, 16, v24
	v_and_b32_e32 v23, 0xffff0000, v25
	v_mul_f32_e32 v21, v21, v21
	v_lshlrev_b32_e32 v22, 16, v25
	v_fmac_f32_e32 v21, v20, v20
	v_mul_f32_e32 v20, v23, v23
	v_lshlrev_b32_e32 v24, 16, v26
	v_and_b32_e32 v25, 0xffff0000, v26
	v_lshlrev_b32_e32 v26, 16, v27
	v_and_b32_e32 v27, 0xffff0000, v27
	v_fmac_f32_e32 v20, v22, v22
	v_add_f32_e32 v20, v21, v20
	v_mul_f32_e32 v21, v25, v25
	v_mul_f32_e32 v22, v27, v27
	v_fmac_f32_e32 v21, v24, v24
	v_fmac_f32_e32 v22, v26, v26
	v_add_f32_e32 v21, v21, v22
	v_add_f32_e32 v20, v20, v21
	v_lshlrev_b32_e32 v21, 16, v16
	v_and_b32_e32 v16, 0xffff0000, v16
	v_lshlrev_b32_e32 v22, 16, v17
	v_and_b32_e32 v17, 0xffff0000, v17
	v_mul_f32_e32 v16, v16, v16
	v_mul_f32_e32 v17, v17, v17
	v_lshlrev_b32_e32 v23, 16, v18
	v_and_b32_e32 v18, 0xffff0000, v18
	v_lshlrev_b32_e32 v24, 16, v19
	v_and_b32_e32 v19, 0xffff0000, v19
	v_fmac_f32_e32 v16, v21, v21
	v_fmac_f32_e32 v17, v22, v22
	v_add_f32_e32 v16, v16, v17
	v_mul_f32_e32 v17, v18, v18
	v_mul_f32_e32 v18, v19, v19
	v_fmac_f32_e32 v17, v23, v23
	v_fmac_f32_e32 v18, v24, v24
	v_add_f32_e32 v17, v17, v18
	v_add_f32_e32 v16, v16, v17
	v_mov_b32_e32 v17, v248
	v_add_f32_e32 v16, v20, v16
	v_mov_b32_e32 v17, v16
	s_nop 1
	v_permlane16_swap_b32_e32 v17, v16
	s_waitcnt lgkmcnt(0)
	v_add_f32_e32 v16, v16, v17
	v_mov_b32_e32 v17, v248
	s_nop 0
	v_mov_b32_e32 v17, v16
	s_nop 1
	v_permlane32_swap_b32_e32 v17, v16
	s_and_saveexec_b64 s[28:29], s[2:3]
	s_cbranch_execz .LBB0_384
	v_lshlrev_b64 v[18:19], 6, v[218:219]
	v_lshl_add_u64 v[18:19], s[10:11], 0, v[18:19]
	v_lshl_add_u64 v[18:19], s[26:27], 2, v[18:19]
	s_lshl_b32 s60, s44, 2
	v_lshl_add_u64 v[18:19], v[18:19], 0, s[60:61]
	s_waitcnt lgkmcnt(0)
	v_add_f32_e32 v16, v16, v17
	global_store_dword v[18:19], v16, off

.LBB0_388:
	s_nop 0
	v_and_b32_e32 v5, 0xffff0000, v8
	v_lshlrev_b32_e32 v4, 16, v8
	v_and_b32_e32 v7, 0xffff0000, v9
	v_mul_f32_e32 v5, v5, v5
	v_lshlrev_b32_e32 v6, 16, v9
	v_fmac_f32_e32 v5, v4, v4
	v_mul_f32_e32 v4, v7, v7
	v_lshlrev_b32_e32 v8, 16, v10
	v_and_b32_e32 v9, 0xffff0000, v10
	v_lshlrev_b32_e32 v10, 16, v11
	v_and_b32_e32 v11, 0xffff0000, v11
	v_fmac_f32_e32 v4, v6, v6
	v_add_f32_e32 v4, v5, v4
	v_mul_f32_e32 v5, v9, v9
	v_mul_f32_e32 v6, v11, v11
	v_fmac_f32_e32 v5, v8, v8
	v_fmac_f32_e32 v6, v10, v10
	v_add_f32_e32 v5, v5, v6
	v_add_f32_e32 v4, v4, v5
	v_lshlrev_b32_e32 v5, 16, v0
	v_and_b32_e32 v0, 0xffff0000, v0
	v_lshlrev_b32_e32 v6, 16, v1
	v_and_b32_e32 v1, 0xffff0000, v1
	v_mul_f32_e32 v0, v0, v0
	v_mul_f32_e32 v1, v1, v1
	v_lshlrev_b32_e32 v7, 16, v2
	v_and_b32_e32 v2, 0xffff0000, v2
	v_lshlrev_b32_e32 v8, 16, v3
	v_and_b32_e32 v3, 0xffff0000, v3
	v_fmac_f32_e32 v0, v5, v5
	v_fmac_f32_e32 v1, v6, v6
	v_add_f32_e32 v0, v0, v1
	v_mul_f32_e32 v1, v2, v2
	v_mul_f32_e32 v2, v3, v3
	v_fmac_f32_e32 v1, v7, v7
	v_fmac_f32_e32 v2, v8, v8
	v_add_f32_e32 v1, v1, v2
	v_add_f32_e32 v0, v0, v1
	v_mov_b32_e32 v1, v248
	v_add_f32_e32 v0, v4, v0
	v_mov_b32_e32 v1, v0
	s_nop 1
	v_permlane16_swap_b32_e32 v1, v0
	s_waitcnt lgkmcnt(0)
	v_add_f32_e32 v0, v0, v1
	v_mov_b32_e32 v1, v248
	s_nop 0
	v_mov_b32_e32 v1, v0
	s_nop 1
	v_permlane32_swap_b32_e32 v1, v0
	s_and_saveexec_b64 s[6:7], s[2:3]
	s_cbranch_execz .LBB0_390
	v_lshlrev_b64 v[2:3], 6, v[212:213]
	v_lshl_add_u64 v[2:3], s[10:11], 0, v[2:3]
	v_lshl_add_u64 v[2:3], s[26:27], 2, v[2:3]
	s_lshl_b32 s60, s44, 2
	v_lshl_add_u64 v[2:3], v[2:3], 0, s[60:61]
	s_waitcnt lgkmcnt(0)
	v_add_f32_e32 v0, v0, v1
	global_store_dword v[2:3], v0, off

.LBB0_637:
	v_lshl_or_b32 v208, s22, 8, v198
	v_lshl_add_u32 v238, s24, 8, v244
	v_ashrrev_i32_e32 v209, 31, v208
	v_lshlrev_b64 v[240:241], 1, v[208:209]
	v_ashrrev_i32_e32 v239, 31, v238
	v_lshl_add_u64 v[122:123], s[10:11], 0, v[240:241]
	v_lshlrev_b64 v[242:243], 11, v[238:239]
	v_lshl_add_u64 v[124:125], v[122:123], 0, v[242:243]
	global_load_dwordx4 v[194:197], v[124:125], off
	global_load_dwordx4 v[186:189], v[124:125], off offset:256
	v_or_b32_e32 v234, 16, v238
	v_ashrrev_i32_e32 v235, 31, v234
	v_or_b32_e32 v230, 32, v238
	v_lshlrev_b64 v[236:237], 11, v[234:235]
	v_ashrrev_i32_e32 v231, 31, v230
	v_or_b32_e32 v226, 48, v238
	v_lshl_add_u64 v[124:125], v[122:123], 0, v[236:237]
	v_lshlrev_b64 v[232:233], 11, v[230:231]
	v_ashrrev_i32_e32 v227, 31, v226
	v_add_u32_e32 v222, 0x80, v238
	global_load_dwordx4 v[182:185], v[124:125], off
	global_load_dwordx4 v[178:181], v[124:125], off offset:256
	v_lshl_add_u64 v[124:125], v[122:123], 0, v[232:233]
	v_lshlrev_b64 v[228:229], 11, v[226:227]
	v_ashrrev_i32_e32 v223, 31, v222
	v_add_u32_e32 v218, 0x90, v238
	global_load_dwordx4 v[174:177], v[124:125], off
	global_load_dwordx4 v[170:173], v[124:125], off offset:256
	v_lshl_add_u64 v[124:125], v[122:123], 0, v[228:229]
	v_lshlrev_b64 v[224:225], 11, v[222:223]
	v_ashrrev_i32_e32 v219, 31, v218
	v_add_u32_e32 v212, 0xa0, v238
	v_add_u32_e32 v210, 0xb0, v238
	global_load_dwordx4 v[166:169], v[124:125], off
	global_load_dwordx4 v[162:165], v[124:125], off offset:256
	v_lshl_add_u64 v[124:125], v[122:123], 0, v[224:225]
	v_lshlrev_b64 v[220:221], 11, v[218:219]
	v_ashrrev_i32_e32 v213, 31, v212
	v_ashrrev_i32_e32 v211, 31, v210
	global_load_dwordx4 v[150:153], v[124:125], off
	global_load_dwordx4 v[146:149], v[124:125], off offset:256
	v_lshl_add_u64 v[124:125], v[122:123], 0, v[220:221]
	v_lshlrev_b64 v[216:217], 11, v[212:213]
	v_lshlrev_b64 v[214:215], 11, v[210:211]
	global_load_dwordx4 v[142:145], v[124:125], off
	global_load_dwordx4 v[138:141], v[124:125], off offset:256
	v_lshl_add_u64 v[124:125], v[122:123], 0, v[216:217]
	v_lshl_add_u64 v[122:123], v[122:123], 0, v[214:215]
	global_load_dwordx4 v[134:137], v[124:125], off
	global_load_dwordx4 v[126:129], v[124:125], off offset:256
	global_load_dwordx4 v[130:133], v[122:123], off
	s_nop 0
	global_load_dwordx4 v[122:125], v[122:123], off offset:256
	s_lshl_b32 s22, s22, 2
	s_ashr_i32 s23, s22, 31
	s_waitcnt vmcnt(0)
	v_lshlrev_b32_e32 v200, 16, v194
	v_and_b32_e32 v194, 0xffff0000, v194
	v_add_f32_e32 v159, v159, v194
	v_lshlrev_b32_e32 v194, 16, v195
	v_add_f32_e32 v160, v160, v194
	v_and_b32_e32 v194, 0xffff0000, v195
	v_add_f32_e32 v161, v161, v194
	v_lshlrev_b32_e32 v194, 16, v196
	v_add_f32_e32 v194, v154, v194
	v_and_b32_e32 v154, 0xffff0000, v196
	v_add_f32_e32 v195, v155, v154
	v_lshlrev_b32_e32 v154, 16, v197
	v_add_f32_e32 v158, v158, v200
	v_add_f32_e32 v196, v156, v154
	v_and_b32_e32 v154, 0xffff0000, v197
	v_add_f32_e32 v157, v157, v154
	v_cvt_pk_bf16_f32 v154, v158, v159
	v_cvt_pk_bf16_f32 v155, v160, v161
	v_lshl_add_u64 v[158:159], s[10:11], 0, v[242:243]
	v_cvt_pk_bf16_f32 v156, v194, v195
	v_cvt_pk_bf16_f32 v157, v196, v157
	v_lshl_add_u64 v[158:159], v[158:159], 0, v[240:241]
	global_store_dwordx4 v[158:159], v[154:157], off sc1
	s_nop 1
	v_lshlrev_b32_e32 v160, 16, v154
	v_and_b32_e32 v154, 0xffff0000, v154
	v_lshlrev_b32_e32 v161, 16, v155
	v_and_b32_e32 v155, 0xffff0000, v155
	v_mul_f32_e32 v154, v154, v154
	v_mul_f32_e32 v155, v155, v155
	v_lshlrev_b32_e32 v194, 16, v156
	v_and_b32_e32 v156, 0xffff0000, v156
	v_lshlrev_b32_e32 v195, 16, v157
	v_and_b32_e32 v157, 0xffff0000, v157
	v_fmac_f32_e32 v154, v160, v160
	v_fmac_f32_e32 v155, v161, v161
	v_add_f32_e32 v154, v154, v155
	v_mul_f32_e32 v155, v156, v156
	v_mul_f32_e32 v156, v157, v157
	v_fmac_f32_e32 v155, v194, v194
	v_fmac_f32_e32 v156, v195, v195
	v_add_f32_e32 v155, v155, v156
	v_add_f32_e32 v154, v154, v155
	v_lshlrev_b32_e32 v155, 16, v186
	v_add_f32_e32 v118, v118, v155
	v_and_b32_e32 v155, 0xffff0000, v186
	v_add_f32_e32 v119, v119, v155
	v_lshlrev_b32_e32 v155, 16, v187
	v_add_f32_e32 v120, v120, v155
	v_and_b32_e32 v155, 0xffff0000, v187
	v_add_f32_e32 v121, v121, v155
	v_lshlrev_b32_e32 v155, 16, v188
	v_add_f32_e32 v155, v114, v155
	v_and_b32_e32 v114, 0xffff0000, v188
	v_add_f32_e32 v156, v115, v114
	v_lshlrev_b32_e32 v114, 16, v189
	v_add_f32_e32 v157, v116, v114
	v_and_b32_e32 v114, 0xffff0000, v189
	v_add_f32_e32 v117, v117, v114
	v_cvt_pk_bf16_f32 v114, v118, v119
	v_cvt_pk_bf16_f32 v115, v120, v121
	v_lshl_add_u64 v[118:119], v[158:159], 0, s[66:67]
	v_cvt_pk_bf16_f32 v116, v155, v156
	v_cvt_pk_bf16_f32 v117, v157, v117
	s_nop 0
	global_store_dwordx4 v[118:119], v[114:117], off sc1
	s_nop 1
	v_lshlrev_b32_e32 v118, 16, v114
	v_and_b32_e32 v114, 0xffff0000, v114
	v_lshlrev_b32_e32 v119, 16, v115
	v_and_b32_e32 v115, 0xffff0000, v115
	v_mul_f32_e32 v114, v114, v114
	v_mul_f32_e32 v115, v115, v115
	v_lshlrev_b32_e32 v120, 16, v116
	v_and_b32_e32 v116, 0xffff0000, v116
	v_lshlrev_b32_e32 v121, 16, v117
	v_and_b32_e32 v117, 0xffff0000, v117
	v_fmac_f32_e32 v114, v118, v118
	v_fmac_f32_e32 v115, v119, v119
	v_add_f32_e32 v114, v114, v115
	v_mul_f32_e32 v115, v116, v116
	v_mul_f32_e32 v116, v117, v117
	v_fmac_f32_e32 v115, v120, v120
	v_fmac_f32_e32 v116, v121, v121
	v_add_f32_e32 v115, v115, v116
	v_add_f32_e32 v114, v114, v115
	v_mov_b32_e32 v115, v248
	v_add_f32_e32 v114, v154, v114
	v_mov_b32_e32 v115, v114
	s_nop 1
	v_permlane16_swap_b32_e32 v115, v114
	s_waitcnt lgkmcnt(0)
	v_add_f32_e32 v114, v114, v115
	v_mov_b32_e32 v115, v248
	s_nop 0
	v_mov_b32_e32 v115, v114
	s_nop 1
	v_permlane32_swap_b32_e32 v115, v114
	s_and_saveexec_b64 s[24:25], s[2:3]
	s_cbranch_execz .LBB0_639
	v_lshlrev_b64 v[116:117], 6, v[238:239]
	v_lshl_add_u64 v[116:117], s[6:7], 0, v[116:117]
	v_lshl_add_u64 v[116:117], s[22:23], 2, v[116:117]
	s_lshl_b32 s60, s44, 2
	v_lshl_add_u64 v[116:117], v[116:117], 0, s[60:61]
	s_waitcnt lgkmcnt(0)
	v_add_f32_e32 v114, v114, v115
	global_store_dword v[116:117], v114, off
.LBB0_639:
	s_or_b64 exec, exec, s[24:25]
	v_lshlrev_b32_e32 v114, 16, v182
	v_add_f32_e32 v110, v110, v114
	v_and_b32_e32 v114, 0xffff0000, v182
	v_add_f32_e32 v111, v111, v114
	v_lshlrev_b32_e32 v114, 16, v183
	v_add_f32_e32 v112, v112, v114
	v_and_b32_e32 v114, 0xffff0000, v183
	v_add_f32_e32 v113, v113, v114
	v_lshlrev_b32_e32 v114, 16, v184
	v_add_f32_e32 v114, v106, v114
	v_and_b32_e32 v106, 0xffff0000, v184
	s_waitcnt lgkmcnt(0)
	v_add_f32_e32 v115, v107, v106
	v_lshlrev_b32_e32 v106, 16, v185
	v_add_f32_e32 v116, v108, v106
	v_and_b32_e32 v106, 0xffff0000, v185
	v_add_f32_e32 v109, v109, v106
	v_cvt_pk_bf16_f32 v106, v110, v111
	v_cvt_pk_bf16_f32 v107, v112, v113
	v_lshl_add_u64 v[110:111], s[10:11], 0, v[236:237]
	v_cvt_pk_bf16_f32 v108, v114, v115
	v_cvt_pk_bf16_f32 v109, v116, v109
	v_lshl_add_u64 v[110:111], v[208:209], 1, v[110:111]
	global_store_dwordx4 v[110:111], v[106:109], off sc1
	s_nop 1
	v_lshlrev_b32_e32 v112, 16, v106
	v_and_b32_e32 v106, 0xffff0000, v106
	v_lshlrev_b32_e32 v113, 16, v107
	v_and_b32_e32 v107, 0xffff0000, v107
	v_mul_f32_e32 v106, v106, v106
	v_mul_f32_e32 v107, v107, v107
	v_lshlrev_b32_e32 v114, 16, v108
	v_and_b32_e32 v108, 0xffff0000, v108
	v_lshlrev_b32_e32 v115, 16, v109
	v_and_b32_e32 v109, 0xffff0000, v109
	v_fmac_f32_e32 v106, v112, v112
	v_fmac_f32_e32 v107, v113, v113
	v_add_f32_e32 v106, v106, v107
	v_mul_f32_e32 v107, v108, v108
	v_mul_f32_e32 v108, v109, v109
	v_fmac_f32_e32 v107, v114, v114
	v_fmac_f32_e32 v108, v115, v115
	v_add_f32_e32 v107, v107, v108
	v_add_f32_e32 v106, v106, v107
	v_lshlrev_b32_e32 v107, 16, v178
	v_add_f32_e32 v102, v102, v107
	v_and_b32_e32 v107, 0xffff0000, v178
	v_add_f32_e32 v103, v103, v107
	v_lshlrev_b32_e32 v107, 16, v179
	v_add_f32_e32 v104, v104, v107
	v_and_b32_e32 v107, 0xffff0000, v179
	v_add_f32_e32 v105, v105, v107
	v_lshlrev_b32_e32 v107, 16, v180
	v_add_f32_e32 v107, v98, v107
	v_and_b32_e32 v98, 0xffff0000, v180
	v_add_f32_e32 v108, v99, v98
	v_lshlrev_b32_e32 v98, 16, v181
	v_add_f32_e32 v109, v100, v98
	v_and_b32_e32 v98, 0xffff0000, v181
	v_add_f32_e32 v101, v101, v98
	v_cvt_pk_bf16_f32 v98, v102, v103
	v_cvt_pk_bf16_f32 v99, v104, v105
	v_lshl_add_u64 v[102:103], v[110:111], 0, s[66:67]
	v_cvt_pk_bf16_f32 v100, v107, v108
	v_cvt_pk_bf16_f32 v101, v109, v101
	s_nop 0
	global_store_dwordx4 v[102:103], v[98:101], off sc1
	s_nop 1
	v_lshlrev_b32_e32 v102, 16, v98
	v_and_b32_e32 v98, 0xffff0000, v98
	v_lshlrev_b32_e32 v103, 16, v99
	v_and_b32_e32 v99, 0xffff0000, v99
	v_mul_f32_e32 v98, v98, v98
	v_mul_f32_e32 v99, v99, v99
	v_lshlrev_b32_e32 v104, 16, v100
	v_and_b32_e32 v100, 0xffff0000, v100
	v_lshlrev_b32_e32 v105, 16, v101
	v_and_b32_e32 v101, 0xffff0000, v101
	v_fmac_f32_e32 v98, v102, v102
	v_fmac_f32_e32 v99, v103, v103
	v_add_f32_e32 v98, v98, v99
	v_mul_f32_e32 v99, v100, v100
	v_mul_f32_e32 v100, v101, v101
	v_fmac_f32_e32 v99, v104, v104
	v_fmac_f32_e32 v100, v105, v105
	v_add_f32_e32 v99, v99, v100
	v_add_f32_e32 v98, v98, v99
	v_mov_b32_e32 v99, v248
	v_add_f32_e32 v98, v106, v98
	v_mov_b32_e32 v99, v98
	s_nop 1
	v_permlane16_swap_b32_e32 v99, v98
	s_waitcnt lgkmcnt(0)
	v_add_f32_e32 v98, v98, v99
	v_mov_b32_e32 v99, v248
	s_nop 0
	v_mov_b32_e32 v99, v98
	s_nop 1
	v_permlane32_swap_b32_e32 v99, v98
	s_and_saveexec_b64 s[24:25], s[2:3]
	s_cbranch_execz .LBB0_641
	v_lshlrev_b64 v[100:101], 6, v[234:235]
	v_lshl_add_u64 v[100:101], s[6:7], 0, v[100:101]
	v_lshl_add_u64 v[100:101], s[22:23], 2, v[100:101]
	s_lshl_b32 s60, s44, 2
	v_lshl_add_u64 v[100:101], v[100:101], 0, s[60:61]
	s_waitcnt lgkmcnt(0)
	v_add_f32_e32 v98, v98, v99
	global_store_dword v[100:101], v98, off
.LBB0_641:
	s_or_b64 exec, exec, s[24:25]
	v_lshlrev_b32_e32 v98, 16, v174
	v_add_f32_e32 v92, v92, v98
	v_and_b32_e32 v98, 0xffff0000, v174
	v_add_f32_e32 v93, v93, v98
	v_lshlrev_b32_e32 v98, 16, v175
	v_add_f32_e32 v94, v94, v98
	v_and_b32_e32 v98, 0xffff0000, v175
	v_add_f32_e32 v95, v95, v98
	v_lshlrev_b32_e32 v98, 16, v176
	v_add_f32_e32 v98, v88, v98
	v_and_b32_e32 v88, 0xffff0000, v176
	s_waitcnt lgkmcnt(0)
	v_add_f32_e32 v99, v89, v88
	v_lshlrev_b32_e32 v88, 16, v177
	v_add_f32_e32 v100, v90, v88
	v_and_b32_e32 v88, 0xffff0000, v177
	v_add_f32_e32 v91, v91, v88
	v_cvt_pk_bf16_f32 v88, v92, v93
	v_cvt_pk_bf16_f32 v89, v94, v95
	v_lshl_add_u64 v[92:93], s[10:11], 0, v[232:233]
	v_cvt_pk_bf16_f32 v90, v98, v99
	v_cvt_pk_bf16_f32 v91, v100, v91
	v_lshl_add_u64 v[92:93], v[208:209], 1, v[92:93]
	global_store_dwordx4 v[92:93], v[88:91], off sc1
	s_nop 1
	v_lshlrev_b32_e32 v94, 16, v88
	v_and_b32_e32 v88, 0xffff0000, v88
	v_lshlrev_b32_e32 v95, 16, v89
	v_and_b32_e32 v89, 0xffff0000, v89
	v_mul_f32_e32 v88, v88, v88
	v_mul_f32_e32 v89, v89, v89
	v_lshlrev_b32_e32 v98, 16, v90
	v_and_b32_e32 v90, 0xffff0000, v90
	v_lshlrev_b32_e32 v99, 16, v91
	v_and_b32_e32 v91, 0xffff0000, v91
	v_fmac_f32_e32 v88, v94, v94
	v_fmac_f32_e32 v89, v95, v95
	v_add_f32_e32 v88, v88, v89
	v_mul_f32_e32 v89, v90, v90
	v_mul_f32_e32 v90, v91, v91
	v_fmac_f32_e32 v89, v98, v98
	v_fmac_f32_e32 v90, v99, v99
	v_add_f32_e32 v89, v89, v90
	v_add_f32_e32 v88, v88, v89
	v_lshlrev_b32_e32 v89, 16, v170
	v_add_f32_e32 v84, v84, v89
	v_and_b32_e32 v89, 0xffff0000, v170
	v_add_f32_e32 v85, v85, v89
	v_lshlrev_b32_e32 v89, 16, v171
	v_add_f32_e32 v86, v86, v89
	v_and_b32_e32 v89, 0xffff0000, v171
	v_add_f32_e32 v87, v87, v89
	v_lshlrev_b32_e32 v89, 16, v172
	v_add_f32_e32 v89, v80, v89
	v_and_b32_e32 v80, 0xffff0000, v172
	v_add_f32_e32 v90, v81, v80
	v_lshlrev_b32_e32 v80, 16, v173
	v_add_f32_e32 v91, v82, v80
	v_and_b32_e32 v80, 0xffff0000, v173
	v_add_f32_e32 v83, v83, v80
	v_cvt_pk_bf16_f32 v80, v84, v85
	v_cvt_pk_bf16_f32 v81, v86, v87
	v_lshl_add_u64 v[84:85], v[92:93], 0, s[66:67]
	v_cvt_pk_bf16_f32 v82, v89, v90
	v_cvt_pk_bf16_f32 v83, v91, v83
	s_nop 0
	global_store_dwordx4 v[84:85], v[80:83], off sc1
	s_nop 1
	v_lshlrev_b32_e32 v84, 16, v80
	v_and_b32_e32 v80, 0xffff0000, v80
	v_lshlrev_b32_e32 v85, 16, v81
	v_and_b32_e32 v81, 0xffff0000, v81
	v_mul_f32_e32 v80, v80, v80
	v_mul_f32_e32 v81, v81, v81
	v_lshlrev_b32_e32 v86, 16, v82
	v_and_b32_e32 v82, 0xffff0000, v82
	v_lshlrev_b32_e32 v87, 16, v83
	v_and_b32_e32 v83, 0xffff0000, v83
	v_fmac_f32_e32 v80, v84, v84
	v_fmac_f32_e32 v81, v85, v85
	v_add_f32_e32 v80, v80, v81
	v_mul_f32_e32 v81, v82, v82
	v_mul_f32_e32 v82, v83, v83
	v_fmac_f32_e32 v81, v86, v86
	v_fmac_f32_e32 v82, v87, v87
	v_add_f32_e32 v81, v81, v82
	v_add_f32_e32 v80, v80, v81
	v_mov_b32_e32 v81, v248
	v_add_f32_e32 v80, v88, v80
	v_mov_b32_e32 v81, v80
	s_nop 1
	v_permlane16_swap_b32_e32 v81, v80
	s_waitcnt lgkmcnt(0)
	v_add_f32_e32 v80, v80, v81
	v_mov_b32_e32 v81, v248
	s_nop 0
	v_mov_b32_e32 v81, v80
	s_nop 1
	v_permlane32_swap_b32_e32 v81, v80
	s_and_saveexec_b64 s[24:25], s[2:3]
	s_cbranch_execz .LBB0_643
	v_lshlrev_b64 v[82:83], 6, v[230:231]
	v_lshl_add_u64 v[82:83], s[6:7], 0, v[82:83]
	v_lshl_add_u64 v[82:83], s[22:23], 2, v[82:83]
	s_lshl_b32 s60, s44, 2
	v_lshl_add_u64 v[82:83], v[82:83], 0, s[60:61]
	s_waitcnt lgkmcnt(0)
	v_add_f32_e32 v80, v80, v81
	global_store_dword v[82:83], v80, off
.LBB0_643:
	s_or_b64 exec, exec, s[24:25]
	v_lshlrev_b32_e32 v80, 16, v166
	v_add_f32_e32 v76, v76, v80
	v_and_b32_e32 v80, 0xffff0000, v166
	v_add_f32_e32 v77, v77, v80
	v_lshlrev_b32_e32 v80, 16, v167
	v_add_f32_e32 v78, v78, v80
	v_and_b32_e32 v80, 0xffff0000, v167
	v_add_f32_e32 v79, v79, v80
	v_lshlrev_b32_e32 v80, 16, v168
	v_add_f32_e32 v80, v72, v80
	v_and_b32_e32 v72, 0xffff0000, v168
	s_waitcnt lgkmcnt(0)
	v_add_f32_e32 v81, v73, v72
	v_lshlrev_b32_e32 v72, 16, v169
	v_add_f32_e32 v82, v74, v72
	v_and_b32_e32 v72, 0xffff0000, v169
	v_add_f32_e32 v75, v75, v72
	v_cvt_pk_bf16_f32 v72, v76, v77
	v_cvt_pk_bf16_f32 v73, v78, v79
	v_lshl_add_u64 v[76:77], s[10:11], 0, v[228:229]
	v_cvt_pk_bf16_f32 v74, v80, v81
	v_cvt_pk_bf16_f32 v75, v82, v75
	v_lshl_add_u64 v[76:77], v[208:209], 1, v[76:77]
	global_store_dwordx4 v[76:77], v[72:75], off sc1
	s_nop 1
	v_lshlrev_b32_e32 v78, 16, v72
	v_and_b32_e32 v72, 0xffff0000, v72
	v_lshlrev_b32_e32 v79, 16, v73
	v_and_b32_e32 v73, 0xffff0000, v73
	v_mul_f32_e32 v72, v72, v72
	v_mul_f32_e32 v73, v73, v73
	v_lshlrev_b32_e32 v80, 16, v74
	v_and_b32_e32 v74, 0xffff0000, v74
	v_lshlrev_b32_e32 v81, 16, v75
	v_and_b32_e32 v75, 0xffff0000, v75
	v_fmac_f32_e32 v72, v78, v78
	v_fmac_f32_e32 v73, v79, v79
	v_add_f32_e32 v72, v72, v73
	v_mul_f32_e32 v73, v74, v74
	v_mul_f32_e32 v74, v75, v75
	v_fmac_f32_e32 v73, v80, v80
	v_fmac_f32_e32 v74, v81, v81
	v_add_f32_e32 v73, v73, v74
	v_add_f32_e32 v72, v72, v73
	v_lshlrev_b32_e32 v73, 16, v162
	v_add_f32_e32 v68, v68, v73
	v_and_b32_e32 v73, 0xffff0000, v162
	v_add_f32_e32 v69, v69, v73
	v_lshlrev_b32_e32 v73, 16, v163
	v_add_f32_e32 v70, v70, v73
	v_and_b32_e32 v73, 0xffff0000, v163
	v_add_f32_e32 v71, v71, v73
	v_lshlrev_b32_e32 v73, 16, v164
	v_add_f32_e32 v73, v64, v73
	v_and_b32_e32 v64, 0xffff0000, v164
	v_add_f32_e32 v74, v65, v64
	v_lshlrev_b32_e32 v64, 16, v165
	v_add_f32_e32 v75, v66, v64
	v_and_b32_e32 v64, 0xffff0000, v165
	v_add_f32_e32 v67, v67, v64
	v_cvt_pk_bf16_f32 v64, v68, v69
	v_cvt_pk_bf16_f32 v65, v70, v71
	v_lshl_add_u64 v[68:69], v[76:77], 0, s[66:67]
	v_cvt_pk_bf16_f32 v66, v73, v74
	v_cvt_pk_bf16_f32 v67, v75, v67
	s_nop 0
	global_store_dwordx4 v[68:69], v[64:67], off sc1
	s_nop 1
	v_lshlrev_b32_e32 v68, 16, v64
	v_and_b32_e32 v64, 0xffff0000, v64
	v_lshlrev_b32_e32 v69, 16, v65
	v_and_b32_e32 v65, 0xffff0000, v65
	v_mul_f32_e32 v64, v64, v64
	v_mul_f32_e32 v65, v65, v65
	v_lshlrev_b32_e32 v70, 16, v66
	v_and_b32_e32 v66, 0xffff0000, v66
	v_lshlrev_b32_e32 v71, 16, v67
	v_and_b32_e32 v67, 0xffff0000, v67
	v_fmac_f32_e32 v64, v68, v68
	v_fmac_f32_e32 v65, v69, v69
	v_add_f32_e32 v64, v64, v65
	v_mul_f32_e32 v65, v66, v66
	v_mul_f32_e32 v66, v67, v67
	v_fmac_f32_e32 v65, v70, v70
	v_fmac_f32_e32 v66, v71, v71
	v_add_f32_e32 v65, v65, v66
	v_add_f32_e32 v64, v64, v65
	v_mov_b32_e32 v65, v248
	v_add_f32_e32 v64, v72, v64
	v_mov_b32_e32 v65, v64
	s_nop 1
	v_permlane16_swap_b32_e32 v65, v64
	s_waitcnt lgkmcnt(0)
	v_add_f32_e32 v64, v64, v65
	v_mov_b32_e32 v65, v248
	s_nop 0
	v_mov_b32_e32 v65, v64
	s_nop 1
	v_permlane32_swap_b32_e32 v65, v64
	s_and_saveexec_b64 s[24:25], s[2:3]
	s_cbranch_execz .LBB0_645
	v_lshlrev_b64 v[66:67], 6, v[226:227]
	v_lshl_add_u64 v[66:67], s[6:7], 0, v[66:67]
	v_lshl_add_u64 v[66:67], s[22:23], 2, v[66:67]
	s_lshl_b32 s60, s44, 2
	v_lshl_add_u64 v[66:67], v[66:67], 0, s[60:61]
	s_waitcnt lgkmcnt(0)
	v_add_f32_e32 v64, v64, v65
	global_store_dword v[66:67], v64, off
.LBB0_645:
	s_or_b64 exec, exec, s[24:25]
	v_lshlrev_b32_e32 v64, 16, v150
	v_add_f32_e32 v60, v60, v64
	v_and_b32_e32 v64, 0xffff0000, v150
	v_add_f32_e32 v61, v61, v64
	v_lshlrev_b32_e32 v64, 16, v151
	v_add_f32_e32 v62, v62, v64
	v_and_b32_e32 v64, 0xffff0000, v151
	v_add_f32_e32 v63, v63, v64
	v_lshlrev_b32_e32 v64, 16, v152
	v_add_f32_e32 v64, v56, v64
	v_and_b32_e32 v56, 0xffff0000, v152
	s_waitcnt lgkmcnt(0)
	v_add_f32_e32 v65, v57, v56
	v_lshlrev_b32_e32 v56, 16, v153
	v_add_f32_e32 v66, v58, v56
	v_and_b32_e32 v56, 0xffff0000, v153
	v_add_f32_e32 v59, v59, v56
	v_cvt_pk_bf16_f32 v56, v60, v61
	v_cvt_pk_bf16_f32 v57, v62, v63
	v_lshl_add_u64 v[60:61], s[10:11], 0, v[224:225]
	v_cvt_pk_bf16_f32 v58, v64, v65
	v_cvt_pk_bf16_f32 v59, v66, v59
	v_lshl_add_u64 v[60:61], v[208:209], 1, v[60:61]
	global_store_dwordx4 v[60:61], v[56:59], off sc1
	s_nop 1
	v_lshlrev_b32_e32 v62, 16, v56
	v_and_b32_e32 v56, 0xffff0000, v56
	v_lshlrev_b32_e32 v63, 16, v57
	v_and_b32_e32 v57, 0xffff0000, v57
	v_mul_f32_e32 v56, v56, v56
	v_mul_f32_e32 v57, v57, v57
	v_lshlrev_b32_e32 v64, 16, v58
	v_and_b32_e32 v58, 0xffff0000, v58
	v_lshlrev_b32_e32 v65, 16, v59
	v_and_b32_e32 v59, 0xffff0000, v59
	v_fmac_f32_e32 v56, v62, v62
	v_fmac_f32_e32 v57, v63, v63
	v_add_f32_e32 v56, v56, v57
	v_mul_f32_e32 v57, v58, v58
	v_mul_f32_e32 v58, v59, v59
	v_fmac_f32_e32 v57, v64, v64
	v_fmac_f32_e32 v58, v65, v65
	v_add_f32_e32 v57, v57, v58
	v_add_f32_e32 v56, v56, v57
	v_lshlrev_b32_e32 v57, 16, v146
	v_add_f32_e32 v52, v52, v57
	v_and_b32_e32 v57, 0xffff0000, v146
	v_add_f32_e32 v53, v53, v57
	v_lshlrev_b32_e32 v57, 16, v147
	v_add_f32_e32 v54, v54, v57
	v_and_b32_e32 v57, 0xffff0000, v147
	v_add_f32_e32 v55, v55, v57
	v_lshlrev_b32_e32 v57, 16, v148
	v_add_f32_e32 v57, v48, v57
	v_and_b32_e32 v48, 0xffff0000, v148
	v_add_f32_e32 v58, v49, v48
	v_lshlrev_b32_e32 v48, 16, v149
	v_add_f32_e32 v59, v50, v48
	v_and_b32_e32 v48, 0xffff0000, v149
	v_add_f32_e32 v51, v51, v48
	v_cvt_pk_bf16_f32 v48, v52, v53
	v_cvt_pk_bf16_f32 v49, v54, v55
	v_lshl_add_u64 v[52:53], v[60:61], 0, s[66:67]
	v_cvt_pk_bf16_f32 v50, v57, v58
	v_cvt_pk_bf16_f32 v51, v59, v51
	s_nop 0
	global_store_dwordx4 v[52:53], v[48:51], off sc1
	s_nop 1
	v_lshlrev_b32_e32 v52, 16, v48
	v_and_b32_e32 v48, 0xffff0000, v48
	v_lshlrev_b32_e32 v53, 16, v49
	v_and_b32_e32 v49, 0xffff0000, v49
	v_mul_f32_e32 v48, v48, v48
	v_mul_f32_e32 v49, v49, v49
	v_lshlrev_b32_e32 v54, 16, v50
	v_and_b32_e32 v50, 0xffff0000, v50
	v_lshlrev_b32_e32 v55, 16, v51
	v_and_b32_e32 v51, 0xffff0000, v51
	v_fmac_f32_e32 v48, v52, v52
	v_fmac_f32_e32 v49, v53, v53
	v_add_f32_e32 v48, v48, v49
	v_mul_f32_e32 v49, v50, v50
	v_mul_f32_e32 v50, v51, v51
	v_fmac_f32_e32 v49, v54, v54
	v_fmac_f32_e32 v50, v55, v55
	v_add_f32_e32 v49, v49, v50
	v_add_f32_e32 v48, v48, v49
	v_mov_b32_e32 v49, v248
	v_add_f32_e32 v48, v56, v48
	v_mov_b32_e32 v49, v48
	s_nop 1
	v_permlane16_swap_b32_e32 v49, v48
	s_waitcnt lgkmcnt(0)
	v_add_f32_e32 v48, v48, v49
	v_mov_b32_e32 v49, v248
	s_nop 0
	v_mov_b32_e32 v49, v48
	s_nop 1
	v_permlane32_swap_b32_e32 v49, v48
	s_and_saveexec_b64 s[24:25], s[2:3]
	s_cbranch_execz .LBB0_647
	v_lshlrev_b64 v[50:51], 6, v[222:223]
	v_lshl_add_u64 v[50:51], s[6:7], 0, v[50:51]
	v_lshl_add_u64 v[50:51], s[22:23], 2, v[50:51]
	s_lshl_b32 s60, s44, 2
	v_lshl_add_u64 v[50:51], v[50:51], 0, s[60:61]
	s_waitcnt lgkmcnt(0)
	v_add_f32_e32 v48, v48, v49
	global_store_dword v[50:51], v48, off
.LBB0_647:
	s_or_b64 exec, exec, s[24:25]
	v_lshlrev_b32_e32 v48, 16, v142
	v_add_f32_e32 v44, v44, v48
	v_and_b32_e32 v48, 0xffff0000, v142
	v_add_f32_e32 v45, v45, v48
	v_lshlrev_b32_e32 v48, 16, v143
	v_add_f32_e32 v46, v46, v48
	v_and_b32_e32 v48, 0xffff0000, v143
	v_add_f32_e32 v47, v47, v48
	v_lshlrev_b32_e32 v48, 16, v144
	v_add_f32_e32 v48, v40, v48
	v_and_b32_e32 v40, 0xffff0000, v144
	s_waitcnt lgkmcnt(0)
	v_add_f32_e32 v49, v41, v40
	v_lshlrev_b32_e32 v40, 16, v145
	v_add_f32_e32 v50, v42, v40
	v_and_b32_e32 v40, 0xffff0000, v145
	v_add_f32_e32 v43, v43, v40
	v_cvt_pk_bf16_f32 v40, v44, v45
	v_cvt_pk_bf16_f32 v41, v46, v47
	v_lshl_add_u64 v[44:45], s[10:11], 0, v[220:221]
	v_cvt_pk_bf16_f32 v42, v48, v49
	v_cvt_pk_bf16_f32 v43, v50, v43
	v_lshl_add_u64 v[44:45], v[208:209], 1, v[44:45]
	global_store_dwordx4 v[44:45], v[40:43], off sc1
	s_nop 1
	v_lshlrev_b32_e32 v46, 16, v40
	v_and_b32_e32 v40, 0xffff0000, v40
	v_lshlrev_b32_e32 v47, 16, v41
	v_and_b32_e32 v41, 0xffff0000, v41
	v_mul_f32_e32 v40, v40, v40
	v_mul_f32_e32 v41, v41, v41
	v_lshlrev_b32_e32 v48, 16, v42
	v_and_b32_e32 v42, 0xffff0000, v42
	v_lshlrev_b32_e32 v49, 16, v43
	v_and_b32_e32 v43, 0xffff0000, v43
	v_fmac_f32_e32 v40, v46, v46
	v_fmac_f32_e32 v41, v47, v47
	v_add_f32_e32 v40, v40, v41
	v_mul_f32_e32 v41, v42, v42
	v_mul_f32_e32 v42, v43, v43
	v_fmac_f32_e32 v41, v48, v48
	v_fmac_f32_e32 v42, v49, v49
	v_add_f32_e32 v41, v41, v42
	v_add_f32_e32 v40, v40, v41
	v_lshlrev_b32_e32 v41, 16, v138
	v_add_f32_e32 v36, v36, v41
	v_and_b32_e32 v41, 0xffff0000, v138
	v_add_f32_e32 v37, v37, v41
	v_lshlrev_b32_e32 v41, 16, v139
	v_add_f32_e32 v38, v38, v41
	v_and_b32_e32 v41, 0xffff0000, v139
	v_add_f32_e32 v39, v39, v41
	v_lshlrev_b32_e32 v41, 16, v140
	v_add_f32_e32 v41, v32, v41
	v_and_b32_e32 v32, 0xffff0000, v140
	v_add_f32_e32 v42, v33, v32
	v_lshlrev_b32_e32 v32, 16, v141
	v_add_f32_e32 v43, v34, v32
	v_and_b32_e32 v32, 0xffff0000, v141
	v_add_f32_e32 v35, v35, v32
	v_cvt_pk_bf16_f32 v32, v36, v37
	v_cvt_pk_bf16_f32 v33, v38, v39
	v_lshl_add_u64 v[36:37], v[44:45], 0, s[66:67]
	v_cvt_pk_bf16_f32 v34, v41, v42
	v_cvt_pk_bf16_f32 v35, v43, v35
	s_nop 0
	global_store_dwordx4 v[36:37], v[32:35], off sc1
	s_nop 1
	v_lshlrev_b32_e32 v36, 16, v32
	v_and_b32_e32 v32, 0xffff0000, v32
	v_lshlrev_b32_e32 v37, 16, v33
	v_and_b32_e32 v33, 0xffff0000, v33
	v_mul_f32_e32 v32, v32, v32
	v_mul_f32_e32 v33, v33, v33
	v_lshlrev_b32_e32 v38, 16, v34
	v_and_b32_e32 v34, 0xffff0000, v34
	v_lshlrev_b32_e32 v39, 16, v35
	v_and_b32_e32 v35, 0xffff0000, v35
	v_fmac_f32_e32 v32, v36, v36
	v_fmac_f32_e32 v33, v37, v37
	v_add_f32_e32 v32, v32, v33
	v_mul_f32_e32 v33, v34, v34
	v_mul_f32_e32 v34, v35, v35
	v_fmac_f32_e32 v33, v38, v38
	v_fmac_f32_e32 v34, v39, v39
	v_add_f32_e32 v33, v33, v34
	v_add_f32_e32 v32, v32, v33
	v_mov_b32_e32 v33, v248
	v_add_f32_e32 v32, v40, v32
	v_mov_b32_e32 v33, v32
	s_nop 1
	v_permlane16_swap_b32_e32 v33, v32
	s_waitcnt lgkmcnt(0)
	v_add_f32_e32 v32, v32, v33
	v_mov_b32_e32 v33, v248
	s_nop 0
	v_mov_b32_e32 v33, v32
	s_nop 1
	v_permlane32_swap_b32_e32 v33, v32
	s_and_saveexec_b64 s[24:25], s[2:3]
	s_cbranch_execz .LBB0_649
	v_lshlrev_b64 v[34:35], 6, v[218:219]
	v_lshl_add_u64 v[34:35], s[6:7], 0, v[34:35]
	v_lshl_add_u64 v[34:35], s[22:23], 2, v[34:35]
	s_lshl_b32 s60, s44, 2
	v_lshl_add_u64 v[34:35], v[34:35], 0, s[60:61]
	s_waitcnt lgkmcnt(0)
	v_add_f32_e32 v32, v32, v33
	global_store_dword v[34:35], v32, off
.LBB0_649:
	s_or_b64 exec, exec, s[24:25]
	v_lshlrev_b32_e32 v32, 16, v134
	v_add_f32_e32 v28, v28, v32
	v_and_b32_e32 v32, 0xffff0000, v134
	v_add_f32_e32 v29, v29, v32
	v_lshlrev_b32_e32 v32, 16, v135
	v_add_f32_e32 v30, v30, v32
	v_and_b32_e32 v32, 0xffff0000, v135
	v_add_f32_e32 v31, v31, v32
	v_lshlrev_b32_e32 v32, 16, v136
	v_add_f32_e32 v32, v24, v32
	v_and_b32_e32 v24, 0xffff0000, v136
	s_waitcnt lgkmcnt(0)
	v_add_f32_e32 v33, v25, v24
	v_lshlrev_b32_e32 v24, 16, v137
	v_add_f32_e32 v34, v26, v24
	v_and_b32_e32 v24, 0xffff0000, v137
	v_add_f32_e32 v27, v27, v24
	v_cvt_pk_bf16_f32 v24, v28, v29
	v_cvt_pk_bf16_f32 v25, v30, v31
	v_lshl_add_u64 v[28:29], s[10:11], 0, v[216:217]
	v_cvt_pk_bf16_f32 v26, v32, v33
	v_cvt_pk_bf16_f32 v27, v34, v27
	v_lshl_add_u64 v[28:29], v[208:209], 1, v[28:29]
	global_store_dwordx4 v[28:29], v[24:27], off sc1
	s_nop 1
	v_lshlrev_b32_e32 v30, 16, v24
	v_and_b32_e32 v24, 0xffff0000, v24
	v_lshlrev_b32_e32 v31, 16, v25
	v_and_b32_e32 v25, 0xffff0000, v25
	v_mul_f32_e32 v24, v24, v24
	v_mul_f32_e32 v25, v25, v25
	v_lshlrev_b32_e32 v32, 16, v26
	v_and_b32_e32 v26, 0xffff0000, v26
	v_lshlrev_b32_e32 v33, 16, v27
	v_and_b32_e32 v27, 0xffff0000, v27
	v_fmac_f32_e32 v24, v30, v30
	v_fmac_f32_e32 v25, v31, v31
	v_add_f32_e32 v24, v24, v25
	v_mul_f32_e32 v25, v26, v26
	v_mul_f32_e32 v26, v27, v27
	v_fmac_f32_e32 v25, v32, v32
	v_fmac_f32_e32 v26, v33, v33
	v_add_f32_e32 v25, v25, v26
	v_add_f32_e32 v24, v24, v25
	v_lshlrev_b32_e32 v25, 16, v126
	v_add_f32_e32 v20, v20, v25
	v_and_b32_e32 v25, 0xffff0000, v126
	v_add_f32_e32 v21, v21, v25
	v_lshlrev_b32_e32 v25, 16, v127
	v_add_f32_e32 v22, v22, v25
	v_and_b32_e32 v25, 0xffff0000, v127
	v_add_f32_e32 v23, v23, v25
	v_lshlrev_b32_e32 v25, 16, v128
	v_add_f32_e32 v25, v16, v25
	v_and_b32_e32 v16, 0xffff0000, v128
	v_add_f32_e32 v26, v17, v16
	v_lshlrev_b32_e32 v16, 16, v129
	v_add_f32_e32 v27, v18, v16
	v_and_b32_e32 v16, 0xffff0000, v129
	v_add_f32_e32 v19, v19, v16
	v_cvt_pk_bf16_f32 v16, v20, v21
	v_cvt_pk_bf16_f32 v17, v22, v23
	v_lshl_add_u64 v[20:21], v[28:29], 0, s[66:67]
	v_cvt_pk_bf16_f32 v18, v25, v26
	v_cvt_pk_bf16_f32 v19, v27, v19
	s_nop 0
	global_store_dwordx4 v[20:21], v[16:19], off sc1
	s_nop 1
	v_lshlrev_b32_e32 v20, 16, v16
	v_and_b32_e32 v16, 0xffff0000, v16
	v_lshlrev_b32_e32 v21, 16, v17
	v_and_b32_e32 v17, 0xffff0000, v17
	v_mul_f32_e32 v16, v16, v16
	v_mul_f32_e32 v17, v17, v17
	v_lshlrev_b32_e32 v22, 16, v18
	v_and_b32_e32 v18, 0xffff0000, v18
	v_lshlrev_b32_e32 v23, 16, v19
	v_and_b32_e32 v19, 0xffff0000, v19
	v_fmac_f32_e32 v16, v20, v20
	v_fmac_f32_e32 v17, v21, v21
	v_add_f32_e32 v16, v16, v17
	v_mul_f32_e32 v17, v18, v18
	v_mul_f32_e32 v18, v19, v19
	v_fmac_f32_e32 v17, v22, v22
	v_fmac_f32_e32 v18, v23, v23
	v_add_f32_e32 v17, v17, v18
	v_add_f32_e32 v16, v16, v17
	v_mov_b32_e32 v17, v248
	v_add_f32_e32 v16, v24, v16
	v_mov_b32_e32 v17, v16
	s_nop 1
	v_permlane16_swap_b32_e32 v17, v16
	s_waitcnt lgkmcnt(0)
	v_add_f32_e32 v16, v16, v17
	v_mov_b32_e32 v17, v248
	s_nop 0
	v_mov_b32_e32 v17, v16
	s_nop 1
	v_permlane32_swap_b32_e32 v17, v16
	s_and_saveexec_b64 s[24:25], s[2:3]
	s_cbranch_execz .LBB0_651
	v_lshlrev_b64 v[18:19], 6, v[212:213]
	v_lshl_add_u64 v[18:19], s[6:7], 0, v[18:19]
	v_lshl_add_u64 v[18:19], s[22:23], 2, v[18:19]
	s_lshl_b32 s60, s44, 2
	v_lshl_add_u64 v[18:19], v[18:19], 0, s[60:61]
	s_waitcnt lgkmcnt(0)
	v_add_f32_e32 v16, v16, v17
	global_store_dword v[18:19], v16, off
.LBB0_651:
	s_or_b64 exec, exec, s[24:25]
	v_lshlrev_b32_e32 v16, 16, v130
	v_add_f32_e32 v12, v12, v16
	v_and_b32_e32 v16, 0xffff0000, v130
	v_add_f32_e32 v13, v13, v16
	v_lshlrev_b32_e32 v16, 16, v131
	v_add_f32_e32 v14, v14, v16
	v_and_b32_e32 v16, 0xffff0000, v131
	v_add_f32_e32 v15, v15, v16
	v_lshlrev_b32_e32 v16, 16, v132
	v_add_f32_e32 v16, v8, v16
	v_and_b32_e32 v8, 0xffff0000, v132
	s_waitcnt lgkmcnt(0)
	v_add_f32_e32 v17, v9, v8
	v_lshlrev_b32_e32 v8, 16, v133
	v_add_f32_e32 v18, v10, v8
	v_and_b32_e32 v8, 0xffff0000, v133
	v_add_f32_e32 v11, v11, v8
	v_cvt_pk_bf16_f32 v8, v12, v13
	v_cvt_pk_bf16_f32 v9, v14, v15
	v_lshl_add_u64 v[12:13], s[10:11], 0, v[214:215]
	v_cvt_pk_bf16_f32 v10, v16, v17
	v_cvt_pk_bf16_f32 v11, v18, v11
	v_lshl_add_u64 v[12:13], v[208:209], 1, v[12:13]
	global_store_dwordx4 v[12:13], v[8:11], off sc1
	s_nop 1
	v_lshlrev_b32_e32 v14, 16, v8
	v_and_b32_e32 v8, 0xffff0000, v8
	v_lshlrev_b32_e32 v15, 16, v9
	v_and_b32_e32 v9, 0xffff0000, v9
	v_mul_f32_e32 v8, v8, v8
	v_mul_f32_e32 v9, v9, v9
	v_lshlrev_b32_e32 v16, 16, v10
	v_and_b32_e32 v10, 0xffff0000, v10
	v_lshlrev_b32_e32 v17, 16, v11
	v_and_b32_e32 v11, 0xffff0000, v11
	v_fmac_f32_e32 v8, v14, v14
	v_fmac_f32_e32 v9, v15, v15
	v_add_f32_e32 v8, v8, v9
	v_mul_f32_e32 v9, v10, v10
	v_mul_f32_e32 v10, v11, v11
	v_fmac_f32_e32 v9, v16, v16
	v_fmac_f32_e32 v10, v17, v17
	v_add_f32_e32 v9, v9, v10
	v_add_f32_e32 v8, v8, v9
	v_lshlrev_b32_e32 v9, 16, v122
	v_add_f32_e32 v4, v4, v9
	v_and_b32_e32 v9, 0xffff0000, v122
	v_add_f32_e32 v5, v5, v9
	v_lshlrev_b32_e32 v9, 16, v123
	v_add_f32_e32 v6, v6, v9
	v_and_b32_e32 v9, 0xffff0000, v123
	v_add_f32_e32 v7, v7, v9
	v_lshlrev_b32_e32 v9, 16, v124
	v_add_f32_e32 v9, v0, v9
	v_and_b32_e32 v0, 0xffff0000, v124
	v_add_f32_e32 v10, v1, v0
	v_lshlrev_b32_e32 v0, 16, v125
	v_add_f32_e32 v11, v2, v0
	v_and_b32_e32 v0, 0xffff0000, v125
	v_add_f32_e32 v3, v3, v0
	v_cvt_pk_bf16_f32 v0, v4, v5
	v_cvt_pk_bf16_f32 v1, v6, v7
	v_lshl_add_u64 v[4:5], v[12:13], 0, s[66:67]
	v_cvt_pk_bf16_f32 v2, v9, v10
	v_cvt_pk_bf16_f32 v3, v11, v3
	s_nop 0
	global_store_dwordx4 v[4:5], v[0:3], off sc1
	s_nop 1
	v_lshlrev_b32_e32 v4, 16, v0
	v_and_b32_e32 v0, 0xffff0000, v0
	v_lshlrev_b32_e32 v5, 16, v1
	v_and_b32_e32 v1, 0xffff0000, v1
	v_mul_f32_e32 v0, v0, v0
	v_mul_f32_e32 v1, v1, v1
	v_lshlrev_b32_e32 v6, 16, v2
	v_and_b32_e32 v2, 0xffff0000, v2
	v_lshlrev_b32_e32 v7, 16, v3
	v_and_b32_e32 v3, 0xffff0000, v3
	v_fmac_f32_e32 v0, v4, v4
	v_fmac_f32_e32 v1, v5, v5
	v_add_f32_e32 v0, v0, v1
	v_mul_f32_e32 v1, v2, v2
	v_mul_f32_e32 v2, v3, v3
	v_fmac_f32_e32 v1, v6, v6
	v_fmac_f32_e32 v2, v7, v7
	v_add_f32_e32 v1, v1, v2
	v_add_f32_e32 v0, v0, v1
	v_mov_b32_e32 v1, v248
	v_add_f32_e32 v0, v8, v0
	v_mov_b32_e32 v1, v0
	s_nop 1
	v_permlane16_swap_b32_e32 v1, v0
	s_waitcnt lgkmcnt(0)
	v_add_f32_e32 v0, v0, v1
	v_mov_b32_e32 v1, v248
	s_nop 0
	v_mov_b32_e32 v1, v0
	s_nop 1
	v_permlane32_swap_b32_e32 v1, v0
	s_and_saveexec_b64 s[24:25], s[2:3]
	s_cbranch_execz .LBB0_653
	v_lshlrev_b64 v[2:3], 6, v[210:211]
	v_lshl_add_u64 v[2:3], s[6:7], 0, v[2:3]
	v_lshl_add_u64 v[2:3], s[22:23], 2, v[2:3]
	s_lshl_b32 s60, s44, 2
	v_lshl_add_u64 v[2:3], v[2:3], 0, s[60:61]
	s_waitcnt lgkmcnt(0)
	v_add_f32_e32 v0, v0, v1
	global_store_dword v[2:3], v0, off
